# sparse-attention compressed branch pass B: key tiles entirely below the per-row limit take a mask-free copy; bit-identical
# baseline (speedup 1.0000x reference)
; DI int crow(int i, int h) { return (i & 3) + 8 * (i >> 2) + 4 * h; }
; DI float shx32(float v) { return __shfl_xor(v, 32); }
; DI void nsa_item(const Params& p_, const EvenBufs& eb_, int b, int g, int tt, unsigned char* smem) {
;     ...
;   for (int kt = 0; kt < nct; ++kt) {
;     TR_<2> kr, vr; tload(kr, Kc + kt * 64 * 64, 64, tid); tload(vr, VcT + kt * 64, 256, tid);
;     __syncthreads();
;     tstore72(kr, sK, tid); tstore68(vr, sV, tid);
;     __syncthreads();
;     f32x16 Sx[2]; qk_tile(sK, qf, Sx, r, h);
; #pragma unroll
;     for (int mt = 0; mt < 2; ++mt) {
; #pragma unroll
;       for (int i = 0; i < 16; ++i) {
;         const bool ok = (kt * 64 + mt * 32 + crow(i, h)) <= nlim;
;         const float pr = __builtin_amdgcn_exp2f(Sx[mt][i] * L2E - mb) * invl;
;         Sx[mt][i] = ok ? pr : 0.f;
;       }
;       float x[4];
; #pragma unroll
;       for (int gg = 0; gg < 4; ++gg) x[gg] = shx32(Sx[mt][4 * gg + 3]);
; #pragma unroll
;       for (int gg = 0; gg < 4; ++gg) {
;         const float prev = h ? x[gg] : (gg ? x[gg > 0 ? gg - 1 : 0] : carry_prev);
;         const float val = Sx[mt][4 * gg] + Sx[mt][4 * gg + 1] + Sx[mt][4 * gg + 2] + Sx[mt][4 * gg + 3] + prev;
;         impW[(wid * 32 + r) * 64 + kt * 16 + mt * 8 + 2 * gg + h] = val;
;       }
;       carry_prev = x[3];
;     }
;     pv_tile<2>(sV, Sx, O, r, h);
.LBB0_1065:
	v_add_u32_e32 v89, s2, v167
	v_add_u32_e32 v89, 59, v89
	v_cmp_gt_i32_e64 s[98:99], v89, v70
	s_cmp_eq_u64 s[98:99], 0
	s_cbranch_scc1 .Lcmpb_fast
	v_lshl_add_u64 v[38:39], s[80:81], 1, v[78:79]
	v_lshl_add_u64 v[34:35], v[38:39], 0, v[114:115]
	v_lshl_add_u64 v[38:39], v[38:39], 0, v[76:77]
	global_load_dwordx4 v[34:37], v[34:35], off
	s_nop 0
	global_load_dwordx4 v[38:41], v[38:39], off
	s_movk_i32 s0, 0xc000
	v_add_co_u32_e64 v42, s[0:1], s0, v82
	s_nop 1
	v_addc_co_u32_e64 v43, s[0:1], -1, v83, s[0:1]
	global_load_dwordx4 v[42:45], v[42:43], off
	s_nop 0
	global_load_dwordx4 v[46:49], v[82:83], off
	v_add_u32_e32 v180, 0x2400, v86
	v_add_u32_e32 v181, 0x3500, v86
	s_barrier
	s_waitcnt vmcnt(3)
	ds_write_b128 v178, v[34:37]
	s_waitcnt vmcnt(2)
	ds_write_b128 v178, v[38:41] offset:4608
	s_waitcnt vmcnt(1)
	ds_write2_b64 v180, v[42:43], v[44:45] offset1:1
	s_waitcnt vmcnt(0)
	ds_write2_b64 v181, v[46:47], v[48:49] offset1:1
	s_waitcnt lgkmcnt(0)
	s_barrier
	ds_read_b128 v[34:37], v179
	ds_read_b128 v[38:41], v179 offset:32
	s_waitcnt lgkmcnt(1)
	v_mfma_f32_32x32x16_bf16 v[50:65], v[34:37], v[138:141], 0
	ds_read_b128 v[34:37], v179 offset:64
	ds_read_b128 v[90:93], v179 offset:4640
	v_add_u32_e32 v89, s2, v167
	v_cmp_le_i32_e64 s[0:1], v89, v70
	v_add_u32_e32 v182, 0x2000, v87
	v_add_u32_e32 v183, 0x3000, v87
	s_addk_i32 s80, 0x1000
	s_waitcnt lgkmcnt(2)
	v_mfma_f32_32x32x16_bf16 v[50:65], v[38:41], v[130:133], v[50:65]
	s_waitcnt lgkmcnt(1)
	v_mfma_f32_32x32x16_bf16 v[50:65], v[34:37], v[134:137], v[50:65]
	ds_read_b128 v[34:37], v179 offset:96
	s_waitcnt lgkmcnt(0)
	v_mfma_f32_32x32x16_bf16 v[50:65], v[34:37], v[142:145], v[50:65]
	ds_read_b128 v[34:37], v179 offset:4608
	s_waitcnt lgkmcnt(0)
	v_mfma_f32_32x32x16_bf16 v[34:49], v[34:37], v[138:141], 0
	s_nop 8
	v_fma_f32 v50, v50, s96, -v72
	v_exp_f32_e32 v50, v50
	s_nop 0
	v_mul_f32_e32 v50, v80, v50
	v_mfma_f32_32x32x16_bf16 v[34:49], v[90:93], v[130:133], v[34:49]
	ds_read_b128 v[90:93], v179 offset:4672
	s_waitcnt lgkmcnt(0)
	v_mfma_f32_32x32x16_bf16 v[34:49], v[90:93], v[134:137], v[34:49]
	ds_read_b128 v[90:93], v179 offset:4704
	s_waitcnt lgkmcnt(0)
	v_mfma_f32_32x32x16_bf16 v[34:49], v[90:93], v[142:145], v[34:49]
	v_cndmask_b32_e64 v91, 0, v50, s[0:1]
	v_fma_f32 v50, v51, s96, -v72
	v_exp_f32_e32 v50, v50
	v_cmp_lt_i32_e64 s[0:1], v89, v70
	v_fma_f32 v51, v53, s96, -v72
	v_exp_f32_e32 v51, v51
	v_mul_f32_e32 v50, v80, v50
	v_cndmask_b32_e64 v92, 0, v50, s[0:1]
	v_fma_f32 v50, v52, s96, -v72
	v_exp_f32_e32 v50, v50
	v_or_b32_e32 v52, 3, v89
	v_or_b32_e32 v53, 2, v89
	v_cmp_le_i32_e64 s[0:1], v52, v69
	v_pk_mul_f32 v[50:51], v[80:81], v[50:51]
	v_or_b32_e32 v52, 9, v89
	v_cndmask_b32_e64 v93, 0, v51, s[0:1]
	v_cmp_le_i32_e64 s[0:1], v53, v70
	v_fma_f32 v51, v55, s96, -v72
	v_exp_f32_e32 v51, v51
	v_cndmask_b32_e64 v94, 0, v50, s[0:1]
	v_fma_f32 v50, v54, s96, -v72
	v_exp_f32_e32 v50, v50
	v_or_b32_e32 v53, 8, v89
	v_cmp_le_i32_e64 s[0:1], v52, v69
	v_or_b32_e32 v52, 11, v89
	v_pk_mul_f32 v[50:51], v[80:81], v[50:51]
	v_or_b32_e32 v54, 17, v89
	v_cndmask_b32_e64 v95, 0, v51, s[0:1]
	v_cmp_le_i32_e64 s[0:1], v53, v70
	v_fma_f32 v51, v57, s96, -v72
	v_exp_f32_e32 v51, v51
	v_cndmask_b32_e64 v96, 0, v50, s[0:1]
	v_fma_f32 v50, v56, s96, -v72
	v_exp_f32_e32 v50, v50
	v_or_b32_e32 v53, 10, v89
	v_cmp_le_i32_e64 s[0:1], v52, v69
	v_or_b32_e32 v55, 16, v89
	v_pk_mul_f32 v[50:51], v[80:81], v[50:51]
	v_or_b32_e32 v56, 19, v89
	v_cndmask_b32_e64 v97, 0, v51, s[0:1]
	v_cmp_le_i32_e64 s[0:1], v53, v70
	v_fma_f32 v51, v59, s96, -v72
	v_exp_f32_e32 v51, v51
	v_cndmask_b32_e64 v98, 0, v50, s[0:1]
	v_fma_f32 v50, v58, s96, -v72
	v_exp_f32_e32 v50, v50
	v_cmp_le_i32_e64 s[0:1], v54, v69
	v_or_b32_e32 v57, 18, v89
	v_or_b32_e32 v58, 25, v89
	v_pk_mul_f32 v[52:53], v[80:81], v[50:51]
	v_or_b32_e32 v59, 24, v89
	v_cndmask_b32_e64 v50, 0, v53, s[0:1]
	v_cmp_le_i32_e64 s[0:1], v55, v70
	v_fma_f32 v53, v61, s96, -v72
	v_exp_f32_e32 v53, v53
	v_cndmask_b32_e64 v51, 0, v52, s[0:1]
	v_fma_f32 v52, v60, s96, -v72
	v_exp_f32_e32 v52, v52
	v_cmp_le_i32_e64 s[0:1], v56, v69
	v_or_b32_e32 v60, 27, v89
	v_or_b32_e32 v61, 26, v89
	v_pk_mul_f32 v[54:55], v[80:81], v[52:53]
	v_add_u32_e32 v90, s2, v32
	v_cndmask_b32_e64 v52, 0, v55, s[0:1]
	v_cmp_le_i32_e64 s[0:1], v57, v70
	v_fma_f32 v55, v63, s96, -v72
	v_exp_f32_e32 v55, v55
	v_cndmask_b32_e64 v53, 0, v54, s[0:1]
	v_fma_f32 v54, v62, s96, -v72
	v_exp_f32_e32 v54, v54
	v_cmp_le_i32_e64 s[0:1], v58, v69
	v_add_f32_e32 v62, v91, v92
	v_add_f32_e32 v62, v94, v62
	v_pk_mul_f32 v[56:57], v[80:81], v[54:55]
	v_add_f32_e32 v62, v93, v62
	v_cndmask_b32_e64 v54, 0, v57, s[0:1]
	v_cmp_le_i32_e64 s[0:1], v59, v70
	v_fma_f32 v57, v65, s96, -v72
	v_exp_f32_e32 v57, v57
	v_cndmask_b32_e64 v55, 0, v56, s[0:1]
	v_fma_f32 v56, v64, s96, -v72
	v_exp_f32_e32 v56, v56
	v_cmp_le_i32_e64 s[0:1], v60, v69
	ds_bpermute_b32 v60, v169, v52
	v_fma_f32 v34, v34, s96, -v72
	v_pk_mul_f32 v[58:59], v[80:81], v[56:57]
	v_fma_f32 v35, v35, s96, -v72
	v_cndmask_b32_e64 v56, 0, v59, s[0:1]
	v_cmp_le_i32_e64 s[0:1], v61, v70
	ds_bpermute_b32 v59, v169, v97
	ds_bpermute_b32 v99, v169, v56
	v_cndmask_b32_e64 v57, 0, v58, s[0:1]
	ds_bpermute_b32 v58, v169, v93
	v_exp_f32_e32 v34, v34
	v_exp_f32_e32 v35, v35
	s_add_i32 s2, s2, 64
	s_cmp_eq_u32 s65, s2
	s_waitcnt lgkmcnt(0)
; DI int crow(int i, int h) { return (i & 3) + 8 * (i >> 2) + 4 * h; }
; DI float shx32(float v) { return __shfl_xor(v, 32); }
; DI void nsa_item(const Params& p_, const EvenBufs& eb_, int b, int g, int tt, unsigned char* smem) {
;     ...
;     f32x16 Sx[2]; qk_tile(sK, qf, Sx, r, h);
; #pragma unroll
;     for (int mt = 0; mt < 2; ++mt) {
; #pragma unroll
;       for (int i = 0; i < 16; ++i) {
;         const bool ok = (kt * 64 + mt * 32 + crow(i, h)) <= nlim;
;         const float pr = __builtin_amdgcn_exp2f(Sx[mt][i] * L2E - mb) * invl;
;         Sx[mt][i] = ok ? pr : 0.f;
;       }
;       float x[4];
; #pragma unroll
;       for (int gg = 0; gg < 4; ++gg) x[gg] = shx32(Sx[mt][4 * gg + 3]);
; #pragma unroll
;       for (int gg = 0; gg < 4; ++gg) {
;         const float prev = h ? x[gg] : (gg ? x[gg > 0 ? gg - 1 : 0] : carry_prev);
;         const float val = Sx[mt][4 * gg] + Sx[mt][4 * gg + 1] + Sx[mt][4 * gg + 2] + Sx[mt][4 * gg + 3] + prev;
;         impW[(wid * 32 + r) * 64 + kt * 16 + mt * 8 + 2 * gg + h] = val;
;       }
;       carry_prev = x[3];
;     }
;     pv_tile<2>(sV, Sx, O, r, h);
	v_cndmask_b32_e32 v61, v58, v88, vcc
	v_add_f32_e32 v61, v62, v61
	v_add_f32_e32 v62, v96, v95
	v_add_f32_e32 v62, v98, v62
	v_cndmask_b32_e32 v58, v59, v58, vcc
	v_add_f32_e32 v62, v97, v62
	v_add_f32_e32 v58, v62, v58
	ds_write2_b32 v90, v61, v58 offset1:2
	v_cndmask_b32_e32 v58, v60, v59, vcc
	v_add_f32_e32 v59, v51, v50
	v_add_f32_e32 v59, v53, v59
	v_add_f32_e32 v59, v52, v59
	v_add_f32_e32 v58, v59, v58
	v_cndmask_b32_e32 v59, v99, v60, vcc
	v_add_f32_e32 v60, v55, v54
	v_add_f32_e32 v60, v57, v60
	v_add_f32_e32 v60, v56, v60
	v_add_f32_e32 v59, v60, v59
	ds_write2_b32 v90, v58, v59 offset0:4 offset1:6
	v_or_b32_e32 v58, 33, v89
	v_or_b32_e32 v59, 32, v89
	v_pk_mul_f32 v[34:35], v[80:81], v[34:35]
	v_cmp_le_i32_e64 s[0:1], v58, v69
	s_nop 1
	v_cndmask_b32_e64 v58, 0, v35, s[0:1]
	v_cmp_le_i32_e64 s[0:1], v59, v70
	v_fma_f32 v35, v37, s96, -v72
	v_exp_f32_e32 v35, v35
	v_cndmask_b32_e64 v59, 0, v34, s[0:1]
	v_fma_f32 v34, v36, s96, -v72
	v_exp_f32_e32 v34, v34
	v_or_b32_e32 v36, 35, v89
	v_or_b32_e32 v37, 34, v89
	v_cmp_le_i32_e64 s[0:1], v36, v69
	v_pk_mul_f32 v[34:35], v[80:81], v[34:35]
	v_or_b32_e32 v36, 41, v89
	v_cndmask_b32_e64 v60, 0, v35, s[0:1]
	v_cmp_le_i32_e64 s[0:1], v37, v70
	v_fma_f32 v35, v39, s96, -v72
	v_exp_f32_e32 v35, v35
	v_cndmask_b32_e64 v61, 0, v34, s[0:1]
	v_fma_f32 v34, v38, s96, -v72
	v_exp_f32_e32 v34, v34
	v_or_b32_e32 v37, 40, v89
	v_cmp_le_i32_e64 s[0:1], v36, v69
	v_or_b32_e32 v36, 43, v89
	v_pk_mul_f32 v[34:35], v[80:81], v[34:35]
	v_add_f32_e32 v38, v59, v58
	v_cndmask_b32_e64 v62, 0, v35, s[0:1]
	v_cmp_le_i32_e64 s[0:1], v37, v70
	v_fma_f32 v35, v41, s96, -v72
	v_exp_f32_e32 v35, v35
	v_cndmask_b32_e64 v63, 0, v34, s[0:1]
	v_fma_f32 v34, v40, s96, -v72
	v_exp_f32_e32 v34, v34
	v_or_b32_e32 v37, 42, v89
	v_cmp_le_i32_e64 s[0:1], v36, v69
	v_or_b32_e32 v36, 49, v89
	v_pk_mul_f32 v[34:35], v[80:81], v[34:35]
	v_add_f32_e32 v38, v61, v38
	v_cndmask_b32_e64 v64, 0, v35, s[0:1]
	v_cmp_le_i32_e64 s[0:1], v37, v70
	v_fma_f32 v35, v43, s96, -v72
	v_exp_f32_e32 v35, v35
	v_cndmask_b32_e64 v65, 0, v34, s[0:1]
	v_fma_f32 v34, v42, s96, -v72
	v_exp_f32_e32 v34, v34
	v_or_b32_e32 v37, 48, v89
	v_cmp_le_i32_e64 s[0:1], v36, v69
	v_or_b32_e32 v36, 51, v89
	v_pk_mul_f32 v[34:35], v[80:81], v[34:35]
	v_add_f32_e32 v38, v60, v38
	v_cndmask_b32_e64 v42, 0, v35, s[0:1]
	v_cmp_le_i32_e64 s[0:1], v37, v70
	v_fma_f32 v35, v45, s96, -v72
	v_exp_f32_e32 v35, v35
	v_cndmask_b32_e64 v43, 0, v34, s[0:1]
	v_fma_f32 v34, v44, s96, -v72
	v_exp_f32_e32 v34, v34
	v_or_b32_e32 v37, 50, v89
	v_cmp_le_i32_e64 s[0:1], v36, v69
	v_or_b32_e32 v36, 57, v89
	v_pk_mul_f32 v[34:35], v[80:81], v[34:35]
	s_nop 0
	v_cndmask_b32_e64 v44, 0, v35, s[0:1]
	v_cmp_le_i32_e64 s[0:1], v37, v70
	v_fma_f32 v35, v47, s96, -v72
	v_exp_f32_e32 v35, v35
	v_cndmask_b32_e64 v45, 0, v34, s[0:1]
	v_fma_f32 v34, v46, s96, -v72
	v_exp_f32_e32 v34, v34
	v_or_b32_e32 v37, 56, v89
	v_cmp_le_i32_e64 s[0:1], v36, v69
	v_or_b32_e32 v36, 59, v89
	v_pk_mul_f32 v[34:35], v[80:81], v[34:35]
	s_nop 0
	v_cndmask_b32_e64 v46, 0, v35, s[0:1]
	v_cmp_le_i32_e64 s[0:1], v37, v70
	v_fma_f32 v35, v49, s96, -v72
	v_exp_f32_e32 v35, v35
	v_cndmask_b32_e64 v47, 0, v34, s[0:1]
	v_fma_f32 v34, v48, s96, -v72
	v_exp_f32_e32 v34, v34
	v_or_b32_e32 v37, 58, v89
	v_cmp_le_i32_e64 s[0:1], v36, v69
	ds_bpermute_b32 v36, v169, v44
	v_pk_mul_f32 v[34:35], v[80:81], v[34:35]
	s_nop 0
	v_cndmask_b32_e64 v48, 0, v35, s[0:1]
	v_cmp_le_i32_e64 s[0:1], v37, v70
	ds_bpermute_b32 v35, v169, v64
	ds_bpermute_b32 v88, v169, v48
	v_cndmask_b32_e64 v49, 0, v34, s[0:1]
	ds_bpermute_b32 v34, v169, v60
	s_mov_b64 s[0:1], 0x80
	v_lshl_add_u64 v[82:83], v[82:83], 0, s[0:1]
	s_waitcnt lgkmcnt(0)
	v_cndmask_b32_e32 v37, v34, v99, vcc
	v_add_f32_e32 v37, v38, v37
	v_add_f32_e32 v38, v63, v62
	v_add_f32_e32 v38, v65, v38
	v_cndmask_b32_e32 v34, v35, v34, vcc
	v_add_f32_e32 v38, v64, v38
	v_add_f32_e32 v34, v38, v34
	ds_write2_b32 v90, v37, v34 offset0:8 offset1:10
	v_cndmask_b32_e32 v34, v36, v35, vcc
	v_add_f32_e32 v35, v43, v42
	v_add_f32_e32 v35, v45, v35
	v_add_f32_e32 v35, v44, v35
	v_add_f32_e32 v34, v35, v34
	v_cndmask_b32_e32 v35, v88, v36, vcc
	v_add_f32_e32 v36, v47, v46
	v_add_f32_e32 v36, v49, v36
	v_add_f32_e32 v36, v48, v36
	v_add_f32_e32 v35, v36, v35
	ds_write2_b32 v90, v34, v35 offset0:12 offset1:14
	v_cvt_pk_bf16_f32 v34, v91, v92
	v_cvt_pk_bf16_f32 v35, v94, v93
	ds_read2_b64 v[90:93], v182 offset0:128 offset1:130
	ds_read2_b64 v[38:41], v182 offset0:132 offset1:134
	v_cvt_pk_bf16_f32 v36, v96, v95
	v_cvt_pk_bf16_f32 v37, v98, v97
	s_waitcnt lgkmcnt(1)
	s_nop 0
	v_mfma_f32_32x32x16_bf16 v[16:31], v[90:93], v[34:37], v[16:31]
	ds_read2_b64 v[90:93], v183 offset0:160 offset1:162
	s_waitcnt lgkmcnt(0)
	v_mfma_f32_32x32x16_bf16 v[0:15], v[90:93], v[34:37], v[0:15]
	v_cvt_pk_bf16_f32 v34, v51, v50
	v_cvt_pk_bf16_f32 v35, v53, v52
	v_cvt_pk_bf16_f32 v36, v55, v54
	v_cvt_pk_bf16_f32 v37, v57, v56
	s_nop 1
	v_mfma_f32_32x32x16_bf16 v[16:31], v[38:41], v[34:37], v[16:31]
	ds_read2_b64 v[38:41], v183 offset0:164 offset1:166
	s_waitcnt lgkmcnt(0)
	v_mfma_f32_32x32x16_bf16 v[0:15], v[38:41], v[34:37], v[0:15]
	ds_read2_b64 v[38:41], v182 offset0:136 offset1:138
	v_cvt_pk_bf16_f32 v34, v59, v58
	v_cvt_pk_bf16_f32 v35, v61, v60
	v_cvt_pk_bf16_f32 v36, v63, v62
	v_cvt_pk_bf16_f32 v37, v65, v64
	s_waitcnt lgkmcnt(0)
	s_nop 0
	v_mfma_f32_32x32x16_bf16 v[16:31], v[38:41], v[34:37], v[16:31]
	ds_read2_b64 v[38:41], v183 offset0:168 offset1:170
	s_waitcnt lgkmcnt(0)
	v_mfma_f32_32x32x16_bf16 v[0:15], v[38:41], v[34:37], v[0:15]
	ds_read2_b64 v[38:41], v182 offset0:140 offset1:142
	v_cvt_pk_bf16_f32 v34, v43, v42
	v_cvt_pk_bf16_f32 v35, v45, v44
	v_cvt_pk_bf16_f32 v36, v47, v46
	v_cvt_pk_bf16_f32 v37, v49, v48
	s_waitcnt lgkmcnt(0)
	s_nop 0
	v_mfma_f32_32x32x16_bf16 v[16:31], v[38:41], v[34:37], v[16:31]
	ds_read2_b64 v[38:41], v183 offset0:172 offset1:174
	s_waitcnt lgkmcnt(0)
	v_mfma_f32_32x32x16_bf16 v[0:15], v[38:41], v[34:37], v[0:15]
	s_cbranch_scc0 .LBB0_1065
; DI void nsa_item(const Params& p_, const EvenBufs& eb_, int b, int g, int tt, unsigned char* smem) {
;     ...
; #pragma unroll
;   for (int dt = 0; dt < 2; ++dt)
; #pragma unroll
;     for (int i = 0; i < 16; ++i) acc[dt][i] = g0 * O[dt][i];
;   __syncthreads();
;   for (int q = 0; q < 8; ++q) {
;     const int rr = wid * 8 + q, tq = t0 + rr, qb = tq >> 6;
;     float v = 0.f;
;     if (lane < nct * 16) v = impW[(0 * 32 + rr) * 64 + lane] + impW[(1 * 32 + rr) * 64 + lane] + impW[(2 * 32 + rr) * 64 + lane] + impW[(3 * 32 + rr) * 64 + lane];
;     const bool forced = (lane == 0) || (lane == qb) || (lane == qb - 1);
;     v = forced ? 1e30f : ((lane > qb) ? -1e30f : v);
;     int rank = 0;
; #pragma unroll
;     for (int jj = 0; jj < 64; ++jj) {
;       const float o = __builtin_bit_cast(float, __builtin_amdgcn_readlane(__builtin_bit_cast(int, v), jj));
;       rank += ((o > v) || (o == v && jj < lane)) ? 1 : 0;
;     }
;     const bool sel = (rank < 16) && (v >= 0.f);
;     const u64 mk = __ballot(sel);
;     if (lane == 0) selm[rr] = mk;
;   }
.Lcmpb_exit:
	s_lshl_b32 s0, s64, 4
	v_writelane_b32 v255, s80, 22
	s_add_i32 s0, s0, 16
	v_cmp_gt_u32_e64 s[0:1], s0, v84
	v_writelane_b32 v255, s81, 23
	v_cmp_ne_u32_e64 s[2:3], 0, v84
	v_writelane_b32 v255, s0, 0
	v_lshlrev_b32_e32 v35, 3, v85
	v_lshlrev_b32_e32 v34, 2, v84
	v_writelane_b32 v255, s1, 1
	v_writelane_b32 v255, s2, 16
	v_lshl_or_b32 v34, v85, 11, v34
	v_subrev_u32_e32 v35, s95, v35
	v_writelane_b32 v255, s3, 17
	v_cmp_lt_u32_e64 s[2:3], 1, v84
	s_mov_b32 s33, 0
	v_cmp_eq_u32_e64 s[0:1], 0, v84
	v_writelane_b32 v255, s2, 2
	v_cmp_lt_u32_e64 s[42:43], 18, v84
	v_cmp_lt_u32_e64 s[44:45], 19, v84
	v_writelane_b32 v255, s3, 3
	v_cmp_lt_u32_e64 s[2:3], 2, v84
	v_cmp_lt_u32_e64 s[46:47], 20, v84
	v_cmp_lt_u32_e64 s[48:49], 21, v84
	v_writelane_b32 v255, s2, 6
	v_cmp_lt_u32_e64 s[50:51], 22, v84
	v_cmp_lt_u32_e64 s[52:53], 23, v84
	v_writelane_b32 v255, s3, 7
	v_cmp_lt_u32_e64 s[2:3], 3, v84
	v_cmp_lt_u32_e64 s[54:55], 24, v84
	v_cmp_lt_u32_e64 s[56:57], 25, v84
	v_writelane_b32 v255, s2, 8
	v_cmp_lt_u32_e64 s[58:59], 26, v84
	v_cmp_lt_u32_e64 s[60:61], 27, v84
	v_writelane_b32 v255, s3, 9
	v_cmp_lt_u32_e64 s[2:3], 4, v84
	v_cmp_lt_u32_e64 s[62:63], 28, v84
	v_cmp_lt_u32_e64 s[64:65], 29, v84
	v_writelane_b32 v255, s2, 10
	v_cmp_lt_u32_e64 s[66:67], 30, v84
	v_cmp_lt_u32_e64 s[68:69], 31, v84
	v_writelane_b32 v255, s3, 11
	v_cmp_lt_u32_e64 s[2:3], 5, v84
	v_cmp_lt_u32_e64 s[70:71], 32, v84
	v_cmp_lt_u32_e64 s[72:73], 33, v84
	v_writelane_b32 v255, s2, 24
	v_cmp_lt_u32_e64 s[74:75], 34, v84
	v_cmp_lt_u32_e64 s[76:77], 35, v84
	v_writelane_b32 v255, s3, 25
	v_cmp_lt_u32_e64 s[2:3], 6, v84
	v_cmp_lt_u32_e64 s[78:79], 36, v84
	v_cmp_lt_u32_e64 s[80:81], 37, v84
	v_writelane_b32 v255, s2, 26
	v_cmp_lt_u32_e64 s[82:83], 38, v84
	v_cmp_lt_u32_e64 s[84:85], 39, v84
	v_writelane_b32 v255, s3, 27
	v_cmp_lt_u32_e64 s[2:3], 7, v84
	v_cmp_lt_u32_e64 s[86:87], 40, v84
	v_cmp_lt_u32_e64 s[88:89], 41, v84
	v_writelane_b32 v255, s2, 28
	v_cmp_lt_u32_e64 s[90:91], 42, v84
	v_cmp_lt_u32_e64 s[92:93], 43, v84
	v_writelane_b32 v255, s3, 29
	v_cmp_lt_u32_e64 s[2:3], 8, v84
	v_lshl_add_u32 v32, v85, 6, v253
	v_add_u32_e32 v34, 0x4800, v34
	v_writelane_b32 v255, s2, 30
	v_add_u32_e32 v35, 0xfe0, v35
	v_cmp_lt_u32_e64 s[96:97], 45, v84
	v_writelane_b32 v255, s3, 31
	v_cmp_lt_u32_e64 s[2:3], 9, v84
	v_cmp_lt_u32_e64 s[4:5], 46, v84
	v_cmp_lt_u32_e64 s[6:7], 48, v84
	v_writelane_b32 v255, s2, 32
	v_cmp_lt_u32_e64 s[8:9], 49, v84
	v_cmp_lt_u32_e64 s[10:11], 50, v84
	v_writelane_b32 v255, s3, 33
	v_cmp_lt_u32_e64 s[2:3], 10, v84
	v_cmp_lt_u32_e64 s[12:13], 51, v84
	v_cmp_lt_u32_e64 s[14:15], 52, v84
	v_writelane_b32 v255, s2, 34
	v_cmp_lt_u32_e64 s[16:17], 53, v84
	v_cmp_lt_u32_e64 s[18:19], 54, v84
	v_writelane_b32 v255, s3, 35
	v_cmp_lt_u32_e64 s[2:3], 11, v84
	v_cmp_lt_u32_e64 s[20:21], 55, v84
	v_cmp_lt_u32_e64 s[22:23], 56, v84
	v_writelane_b32 v255, s2, 36
	v_cmp_lt_u32_e64 s[24:25], 57, v84
	v_cmp_lt_u32_e64 s[26:27], 58, v84
	v_writelane_b32 v255, s3, 37
	v_cmp_lt_u32_e64 s[2:3], 12, v84
	v_cmp_lt_u32_e64 s[28:29], 59, v84
	v_cmp_lt_u32_e64 s[30:31], 60, v84
	v_writelane_b32 v255, s2, 38
	v_cmp_lt_u32_e64 s[34:35], 61, v84
	v_cmp_eq_u32_e64 s[36:37], 63, v84
	v_writelane_b32 v255, s3, 39
	v_cmp_lt_u32_e64 s[2:3], 13, v84
	s_barrier
	s_nop 0
	v_writelane_b32 v255, s2, 40
	s_nop 1
	v_writelane_b32 v255, s3, 41
	v_cmp_lt_u32_e64 s[2:3], 14, v84
	s_nop 1
	v_writelane_b32 v255, s2, 42
	s_nop 1
	v_writelane_b32 v255, s3, 43
	v_cmp_lt_u32_e64 s[2:3], 15, v84
	s_nop 1
	v_writelane_b32 v255, s2, 44
	s_nop 1
	v_writelane_b32 v255, s3, 45
	v_cmp_lt_u32_e64 s[2:3], 16, v84
	s_nop 1
	v_writelane_b32 v255, s2, 46
	s_nop 1
	v_writelane_b32 v255, s3, 47
	v_cmp_lt_u32_e64 s[2:3], 17, v84
	s_nop 1
	v_writelane_b32 v255, s2, 48
	s_nop 1
	v_writelane_b32 v255, s3, 49
	v_writelane_b32 v255, s95, 50
	v_cmp_lt_u32_e64 s[94:95], 44, v84
	v_cmp_lt_u32_e64 s[2:3], 47, v84
	s_branch .LBB0_1068

; DI int crow(int i, int h) { return (i & 3) + 8 * (i >> 2) + 4 * h; }
; DI float shx32(float v) { return __shfl_xor(v, 32); }
; DI void nsa_item(const Params& p_, const EvenBufs& eb_, int b, int g, int tt, unsigned char* smem) {
;     ...
;   for (int kt = 0; kt < nct; ++kt) {
;     TR_<2> kr, vr; tload(kr, Kc + kt * 64 * 64, 64, tid); tload(vr, VcT + kt * 64, 256, tid);
;     __syncthreads();
;     tstore72(kr, sK, tid); tstore68(vr, sV, tid);
;     __syncthreads();
;     f32x16 Sx[2]; qk_tile(sK, qf, Sx, r, h);
; #pragma unroll
;     for (int mt = 0; mt < 2; ++mt) {
; #pragma unroll
;       for (int i = 0; i < 16; ++i) {
;         const bool ok = (kt * 64 + mt * 32 + crow(i, h)) <= nlim;
;         const float pr = __builtin_amdgcn_exp2f(Sx[mt][i] * L2E - mb) * invl;
;         Sx[mt][i] = ok ? pr : 0.f;
;       }
;       float x[4];
; #pragma unroll
;       for (int gg = 0; gg < 4; ++gg) x[gg] = shx32(Sx[mt][4 * gg + 3]);
.Lcmpb_fast:
	v_lshl_add_u64 v[38:39], s[80:81], 1, v[78:79]
	v_lshl_add_u64 v[34:35], v[38:39], 0, v[114:115]
	v_lshl_add_u64 v[38:39], v[38:39], 0, v[76:77]
	global_load_dwordx4 v[34:37], v[34:35], off
	s_nop 0
	global_load_dwordx4 v[38:41], v[38:39], off
	s_movk_i32 s0, 0xc000
	v_add_co_u32_e64 v42, s[0:1], s0, v82
	s_nop 1
	v_addc_co_u32_e64 v43, s[0:1], -1, v83, s[0:1]
	global_load_dwordx4 v[42:45], v[42:43], off
	s_nop 0
	global_load_dwordx4 v[46:49], v[82:83], off
	v_add_u32_e32 v180, 0x2400, v86
	v_add_u32_e32 v181, 0x3500, v86
	s_barrier
	s_waitcnt vmcnt(3)
	ds_write_b128 v178, v[34:37]
	s_waitcnt vmcnt(2)
	ds_write_b128 v178, v[38:41] offset:4608
	s_waitcnt vmcnt(1)
	ds_write2_b64 v180, v[42:43], v[44:45] offset1:1
	s_waitcnt vmcnt(0)
	ds_write2_b64 v181, v[46:47], v[48:49] offset1:1
	s_waitcnt lgkmcnt(0)
	s_barrier
	ds_read_b128 v[34:37], v179
	ds_read_b128 v[38:41], v179 offset:32
	s_waitcnt lgkmcnt(1)
	v_mfma_f32_32x32x16_bf16 v[50:65], v[34:37], v[138:141], 0
	ds_read_b128 v[34:37], v179 offset:64
	ds_read_b128 v[90:93], v179 offset:4640
	v_add_u32_e32 v89, s2, v167
	v_add_u32_e32 v182, 0x2000, v87
	v_add_u32_e32 v183, 0x3000, v87
	s_addk_i32 s80, 0x1000
	s_waitcnt lgkmcnt(2)
	v_mfma_f32_32x32x16_bf16 v[50:65], v[38:41], v[130:133], v[50:65]
	s_waitcnt lgkmcnt(1)
	v_mfma_f32_32x32x16_bf16 v[50:65], v[34:37], v[134:137], v[50:65]
	ds_read_b128 v[34:37], v179 offset:96
	s_waitcnt lgkmcnt(0)
	v_mfma_f32_32x32x16_bf16 v[50:65], v[34:37], v[142:145], v[50:65]
	ds_read_b128 v[34:37], v179 offset:4608
	s_waitcnt lgkmcnt(0)
	v_mfma_f32_32x32x16_bf16 v[34:49], v[34:37], v[138:141], 0
	s_nop 8
	v_fma_f32 v50, v50, s96, -v72
	v_exp_f32_e32 v50, v50
	s_nop 0
	v_mul_f32_e32 v50, v80, v50
	v_mfma_f32_32x32x16_bf16 v[34:49], v[90:93], v[130:133], v[34:49]
	ds_read_b128 v[90:93], v179 offset:4672
	s_waitcnt lgkmcnt(0)
	v_mfma_f32_32x32x16_bf16 v[34:49], v[90:93], v[134:137], v[34:49]
	ds_read_b128 v[90:93], v179 offset:4704
	s_waitcnt lgkmcnt(0)
	v_mfma_f32_32x32x16_bf16 v[34:49], v[90:93], v[142:145], v[34:49]
	v_mov_b32_e32 v91, v50
	v_fma_f32 v50, v51, s96, -v72
	v_exp_f32_e32 v50, v50
	v_fma_f32 v51, v53, s96, -v72
	v_exp_f32_e32 v51, v51
	v_mul_f32_e32 v50, v80, v50
	v_mov_b32_e32 v92, v50
	v_fma_f32 v50, v52, s96, -v72
	v_exp_f32_e32 v50, v50
	s_nop 0
	v_pk_mul_f32 v[50:51], v[80:81], v[50:51]
	v_mov_b32_e32 v93, v51
	v_fma_f32 v51, v55, s96, -v72
	v_exp_f32_e32 v51, v51
	v_mov_b32_e32 v94, v50
	v_fma_f32 v50, v54, s96, -v72
	v_exp_f32_e32 v50, v50
	s_nop 0
	v_pk_mul_f32 v[50:51], v[80:81], v[50:51]
	v_mov_b32_e32 v95, v51
	v_fma_f32 v51, v57, s96, -v72
	v_exp_f32_e32 v51, v51
	v_mov_b32_e32 v96, v50
	v_fma_f32 v50, v56, s96, -v72
	v_exp_f32_e32 v50, v50
	s_nop 0
	v_pk_mul_f32 v[50:51], v[80:81], v[50:51]
	v_mov_b32_e32 v97, v51
	v_fma_f32 v51, v59, s96, -v72
	v_exp_f32_e32 v51, v51
	v_mov_b32_e32 v98, v50
	v_fma_f32 v50, v58, s96, -v72
	v_exp_f32_e32 v50, v50
	s_nop 0
	v_pk_mul_f32 v[52:53], v[80:81], v[50:51]
	v_mov_b32_e32 v50, v53
	v_fma_f32 v53, v61, s96, -v72
	v_exp_f32_e32 v53, v53
	v_mov_b32_e32 v51, v52
	v_fma_f32 v52, v60, s96, -v72
	v_exp_f32_e32 v52, v52
	s_nop 0
	v_pk_mul_f32 v[54:55], v[80:81], v[52:53]
	v_add_u32_e32 v90, s2, v32
	v_mov_b32_e32 v52, v55
	v_fma_f32 v55, v63, s96, -v72
	v_exp_f32_e32 v55, v55
	v_mov_b32_e32 v53, v54
	v_fma_f32 v54, v62, s96, -v72
	v_exp_f32_e32 v54, v54
	v_add_f32_e32 v62, v91, v92
	v_add_f32_e32 v62, v94, v62
	v_pk_mul_f32 v[56:57], v[80:81], v[54:55]
	v_add_f32_e32 v62, v93, v62
	v_mov_b32_e32 v54, v57
	v_fma_f32 v57, v65, s96, -v72
	v_exp_f32_e32 v57, v57
	v_mov_b32_e32 v55, v56
	v_fma_f32 v56, v64, s96, -v72
	v_exp_f32_e32 v56, v56
	ds_bpermute_b32 v60, v169, v52
	v_fma_f32 v34, v34, s96, -v72
	v_pk_mul_f32 v[58:59], v[80:81], v[56:57]
	v_fma_f32 v35, v35, s96, -v72
	v_mov_b32_e32 v56, v59
	ds_bpermute_b32 v59, v169, v97
	ds_bpermute_b32 v99, v169, v56
	v_mov_b32_e32 v57, v58
	ds_bpermute_b32 v58, v169, v93
	v_exp_f32_e32 v34, v34
	v_exp_f32_e32 v35, v35
	s_add_i32 s2, s2, 64
	s_cmp_eq_u32 s65, s2
	s_waitcnt lgkmcnt(0)
; DI int crow(int i, int h) { return (i & 3) + 8 * (i >> 2) + 4 * h; }
; DI float shx32(float v) { return __shfl_xor(v, 32); }
; DI void nsa_item(const Params& p_, const EvenBufs& eb_, int b, int g, int tt, unsigned char* smem) {
;     ...
;     f32x16 Sx[2]; qk_tile(sK, qf, Sx, r, h);
; #pragma unroll
;     for (int mt = 0; mt < 2; ++mt) {
; #pragma unroll
;       for (int i = 0; i < 16; ++i) {
;         const bool ok = (kt * 64 + mt * 32 + crow(i, h)) <= nlim;
;         const float pr = __builtin_amdgcn_exp2f(Sx[mt][i] * L2E - mb) * invl;
;         Sx[mt][i] = ok ? pr : 0.f;
;       }
;       float x[4];
; #pragma unroll
;       for (int gg = 0; gg < 4; ++gg) x[gg] = shx32(Sx[mt][4 * gg + 3]);
; #pragma unroll
;       for (int gg = 0; gg < 4; ++gg) {
;         const float prev = h ? x[gg] : (gg ? x[gg > 0 ? gg - 1 : 0] : carry_prev);
;         const float val = Sx[mt][4 * gg] + Sx[mt][4 * gg + 1] + Sx[mt][4 * gg + 2] + Sx[mt][4 * gg + 3] + prev;
;         impW[(wid * 32 + r) * 64 + kt * 16 + mt * 8 + 2 * gg + h] = val;
;       }
;       carry_prev = x[3];
;     }
;     pv_tile<2>(sV, Sx, O, r, h);
	v_cndmask_b32_e32 v61, v58, v88, vcc
	v_add_f32_e32 v61, v62, v61
	v_add_f32_e32 v62, v96, v95
	v_add_f32_e32 v62, v98, v62
	v_cndmask_b32_e32 v58, v59, v58, vcc
	v_add_f32_e32 v62, v97, v62
	v_add_f32_e32 v58, v62, v58
	ds_write2_b32 v90, v61, v58 offset1:2
	v_cndmask_b32_e32 v58, v60, v59, vcc
	v_add_f32_e32 v59, v51, v50
	v_add_f32_e32 v59, v53, v59
	v_add_f32_e32 v59, v52, v59
	v_add_f32_e32 v58, v59, v58
	v_cndmask_b32_e32 v59, v99, v60, vcc
	v_add_f32_e32 v60, v55, v54
	v_add_f32_e32 v60, v57, v60
	v_add_f32_e32 v60, v56, v60
	v_add_f32_e32 v59, v60, v59
	ds_write2_b32 v90, v58, v59 offset0:4 offset1:6
	v_pk_mul_f32 v[34:35], v[80:81], v[34:35]
	s_nop 1
	v_mov_b32_e32 v58, v35
	v_fma_f32 v35, v37, s96, -v72
	v_exp_f32_e32 v35, v35
	v_mov_b32_e32 v59, v34
	v_fma_f32 v34, v36, s96, -v72
	v_exp_f32_e32 v34, v34
	s_nop 0
	v_pk_mul_f32 v[34:35], v[80:81], v[34:35]
	v_mov_b32_e32 v60, v35
	v_fma_f32 v35, v39, s96, -v72
	v_exp_f32_e32 v35, v35
	v_mov_b32_e32 v61, v34
	v_fma_f32 v34, v38, s96, -v72
	v_exp_f32_e32 v34, v34
	s_nop 0
	v_pk_mul_f32 v[34:35], v[80:81], v[34:35]
	v_add_f32_e32 v38, v59, v58
	v_mov_b32_e32 v62, v35
	v_fma_f32 v35, v41, s96, -v72
	v_exp_f32_e32 v35, v35
	v_mov_b32_e32 v63, v34
	v_fma_f32 v34, v40, s96, -v72
	v_exp_f32_e32 v34, v34
	s_nop 0
	v_pk_mul_f32 v[34:35], v[80:81], v[34:35]
	v_add_f32_e32 v38, v61, v38
	v_mov_b32_e32 v64, v35
	v_fma_f32 v35, v43, s96, -v72
	v_exp_f32_e32 v35, v35
	v_mov_b32_e32 v65, v34
	v_fma_f32 v34, v42, s96, -v72
	v_exp_f32_e32 v34, v34
	s_nop 0
	v_pk_mul_f32 v[34:35], v[80:81], v[34:35]
	v_add_f32_e32 v38, v60, v38
	v_mov_b32_e32 v42, v35
	v_fma_f32 v35, v45, s96, -v72
	v_exp_f32_e32 v35, v35
	v_mov_b32_e32 v43, v34
	v_fma_f32 v34, v44, s96, -v72
	v_exp_f32_e32 v34, v34
	s_nop 0
	v_pk_mul_f32 v[34:35], v[80:81], v[34:35]
	s_nop 0
	v_mov_b32_e32 v44, v35
	v_fma_f32 v35, v47, s96, -v72
	v_exp_f32_e32 v35, v35
	v_mov_b32_e32 v45, v34
	v_fma_f32 v34, v46, s96, -v72
	v_exp_f32_e32 v34, v34
	s_nop 0
	v_pk_mul_f32 v[34:35], v[80:81], v[34:35]
	s_nop 0
	v_mov_b32_e32 v46, v35
	v_fma_f32 v35, v49, s96, -v72
	v_exp_f32_e32 v35, v35
	v_mov_b32_e32 v47, v34
	v_fma_f32 v34, v48, s96, -v72
	v_exp_f32_e32 v34, v34
	ds_bpermute_b32 v36, v169, v44
	v_pk_mul_f32 v[34:35], v[80:81], v[34:35]
	s_nop 0
	v_mov_b32_e32 v48, v35
	ds_bpermute_b32 v35, v169, v64
	ds_bpermute_b32 v88, v169, v48
	v_mov_b32_e32 v49, v34
	ds_bpermute_b32 v34, v169, v60
	s_mov_b64 s[0:1], 0x80
	v_lshl_add_u64 v[82:83], v[82:83], 0, s[0:1]
	s_waitcnt lgkmcnt(0)
	v_cndmask_b32_e32 v37, v34, v99, vcc
	v_add_f32_e32 v37, v38, v37
	v_add_f32_e32 v38, v63, v62
	v_add_f32_e32 v38, v65, v38
	v_cndmask_b32_e32 v34, v35, v34, vcc
	v_add_f32_e32 v38, v64, v38
	v_add_f32_e32 v34, v38, v34
	ds_write2_b32 v90, v37, v34 offset0:8 offset1:10
	v_cndmask_b32_e32 v34, v36, v35, vcc
	v_add_f32_e32 v35, v43, v42
	v_add_f32_e32 v35, v45, v35
	v_add_f32_e32 v35, v44, v35
	v_add_f32_e32 v34, v35, v34
	v_cndmask_b32_e32 v35, v88, v36, vcc
	v_add_f32_e32 v36, v47, v46
	v_add_f32_e32 v36, v49, v36
	v_add_f32_e32 v36, v48, v36
	v_add_f32_e32 v35, v36, v35
	ds_write2_b32 v90, v34, v35 offset0:12 offset1:14
	v_cvt_pk_bf16_f32 v34, v91, v92
	v_cvt_pk_bf16_f32 v35, v94, v93
	ds_read2_b64 v[90:93], v182 offset0:128 offset1:130
	ds_read2_b64 v[38:41], v182 offset0:132 offset1:134
	v_cvt_pk_bf16_f32 v36, v96, v95
	v_cvt_pk_bf16_f32 v37, v98, v97
	s_waitcnt lgkmcnt(1)
	s_nop 0
	v_mfma_f32_32x32x16_bf16 v[16:31], v[90:93], v[34:37], v[16:31]
	ds_read2_b64 v[90:93], v183 offset0:160 offset1:162
	s_waitcnt lgkmcnt(0)
	v_mfma_f32_32x32x16_bf16 v[0:15], v[90:93], v[34:37], v[0:15]
	v_cvt_pk_bf16_f32 v34, v51, v50
	v_cvt_pk_bf16_f32 v35, v53, v52
	v_cvt_pk_bf16_f32 v36, v55, v54
	v_cvt_pk_bf16_f32 v37, v57, v56
	s_nop 1
	s_nop 0
	v_mfma_f32_32x32x16_bf16 v[16:31], v[38:41], v[34:37], v[16:31]
	ds_read2_b64 v[38:41], v183 offset0:164 offset1:166
	s_waitcnt lgkmcnt(0)
	v_mfma_f32_32x32x16_bf16 v[0:15], v[38:41], v[34:37], v[0:15]
	ds_read2_b64 v[38:41], v182 offset0:136 offset1:138
	v_cvt_pk_bf16_f32 v34, v59, v58
	v_cvt_pk_bf16_f32 v35, v61, v60
	v_cvt_pk_bf16_f32 v36, v63, v62
	v_cvt_pk_bf16_f32 v37, v65, v64
	s_waitcnt lgkmcnt(0)
	s_nop 0
	v_mfma_f32_32x32x16_bf16 v[16:31], v[38:41], v[34:37], v[16:31]
	ds_read2_b64 v[38:41], v183 offset0:168 offset1:170
	s_waitcnt lgkmcnt(0)
	v_mfma_f32_32x32x16_bf16 v[0:15], v[38:41], v[34:37], v[0:15]
	ds_read2_b64 v[38:41], v182 offset0:140 offset1:142
	v_cvt_pk_bf16_f32 v34, v43, v42
	v_cvt_pk_bf16_f32 v35, v45, v44
	v_cvt_pk_bf16_f32 v36, v47, v46
	v_cvt_pk_bf16_f32 v37, v49, v48
	s_waitcnt lgkmcnt(0)
	s_nop 0
	v_mfma_f32_32x32x16_bf16 v[16:31], v[38:41], v[34:37], v[16:31]
	ds_read2_b64 v[38:41], v183 offset0:172 offset1:174
	s_waitcnt lgkmcnt(0)
	v_mfma_f32_32x32x16_bf16 v[0:15], v[38:41], v[34:37], v[0:15]
	s_cbranch_scc0 .LBB0_1065
	s_branch .Lcmpb_exit
